# full stack + hand-scheduled unorm8 gate epilogue variant (folded -log2e scale, packed +1.0, SDWA-preserve byte packing: 361 fewer VALU per wave per gate tile)
# baseline (speedup 1.0000x reference)
; __device__ __forceinline__ unsigned cvt_pk_bf16(float lo, float hi) { const bf16x2_t r = __builtin_convertvector((f32x2){lo, hi}, bf16x2_t); return __builtin_bit_cast(unsigned, r); }
; __device__ __forceinline__ float bf_lo(unsigned u) { return __uint_as_float(u << 16); }
; __device__ __forceinline__ float bf_hi(unsigned u) { return __uint_as_float(u & 0xffff0000u); }
; __device__ __forceinline__ float sigmoid_f(float x) { return __builtin_amdgcn_rcpf(1.0f + __builtin_amdgcn_exp2f(-1.4426950409f * x)); }
; __device__ __forceinline__ float silu_f(float x) { return x * sigmoid_f(x); }
; __device__ __forceinline__ u32x4 pack8(f32x4 a, f32x4 b) { u32x4 w; w.x = cvt_pk_bf16(a[0], a[1]); w.y = cvt_pk_bf16(a[2], a[3]); w.z = cvt_pk_bf16(b[0], b[1]); w.w = cvt_pk_bf16(b[2], b[3]); return w; }
; __device__ __forceinline__ void unpack8(u32x4 g, f32x4& a, f32x4& b) { a = (f32x4){bf_lo(g.x), bf_hi(g.x), bf_lo(g.y), bf_hi(g.y)}; b = (f32x4){bf_lo(g.z), bf_hi(g.z), bf_lo(g.w), bf_hi(g.w)}; }
;     __device__ __forceinline__ void body_gate(f32x4 (&acc)[2][2][4][2], const Unit& u, int wr, int wc, int fr, int fq, int gbase, const float (&rsv)[2][4]) const {
;         EPI_ROWS_BEGIN
;             const float rs = rsv[ai][m];
; #pragma unroll
;             for (int bj = 0; bj < 2; ++bj) { if (u.half != 0 && bj == 1) continue;
;                 const int gcol = gbase + (bj + (u.half == 2 ? 1 : 0)) * 128 + wc * 32 + 8 * fq;
;                 f32x4 v0 = acc[ai][bj][m][0] * rs, v1 = acc[ai][bj][m][1] * rs;
; #pragma unroll
;                 for (int j = 0; j < 4; ++j) { v0[j] = sigmoid_f(v0[j]); v1[j] = sigmoid_f(v1[j]); }
;                 u32x2 w; w.x = pk_unorm8(v0); w.y = pk_unorm8(v1);
;                 *(u32x2*)((unsigned char*)P + (size_t)row * ROWB + GATE_B0 + gcol) = w;
.LBB0_200:
	s_cmp_gt_u32 s52, 15
	s_cbranch_scc0 .LBB0_218
	s_cmp_gt_u32 s52, 19
	s_cbranch_scc0 .LBB0_215
	s_cmp_gt_u32 s52, 23
	s_cbranch_scc0 .LBB0_212
	s_cmp_gt_u32 s52, 31
	s_cbranch_scc0 .LBB0_209
	v_mov_b32_e32 v159, v158
	v_pk_mul_f32 v[178:179], v[126:127], v[158:159] op_sel_hi:[1,0]
	s_lshl_b32 s6, s52, 8
	v_mul_f32_e32 v160, 0xbfb8aa3b, v178
	v_exp_f32_e32 v170, v160
	v_mad_i64_i32 v[168:169], s[4:5], v154, s33, 0
	v_pk_mul_f32 v[174:175], v[128:129], v[158:159] op_sel_hi:[1,0]
	v_add_f32_e32 v170, 1.0, v170
	v_rcp_f32_e32 v180, v170
	v_pk_mul_f32 v[160:161], v[124:125], v[158:159] op_sel_hi:[1,0]
	v_pk_mul_f32 v[176:177], v[122:123], v[158:159] op_sel_hi:[1,0]
	s_cmp_gt_u32 s52, 35
	v_lshlrev_b32_e32 v216, 3, v210
	s_mov_b64 s[4:5], -1
	v_lshl_add_u64 v[172:173], s[68:69], 0, v[168:169]
	v_mul_f32_e32 v218, 0xbfb8aa3b, v176
	v_mul_f32_e32 v217, 0xbfb8aa3b, v179
	v_mul_f32_e32 v215, 0xbfb8aa3b, v177
	v_mul_f32_e32 v214, 0xbfb8aa3b, v174
	v_mul_f32_e32 v213, 0xbfb8aa3b, v160
	v_mul_f32_e32 v212, 0xbfb8aa3b, v175
	v_mul_f32_e32 v211, 0xbfb8aa3b, v161
	v_pk_mul_f32 v[170:171], v[118:119], v[158:159]
	v_pk_mul_f32 v[168:169], v[110:111], v[158:159]
	s_cbranch_scc0 .LBB0_206
	s_mov_b32 s8, 0x437f0000
	s_add_i32 s4, s27, s6
	s_lshr_b32 s98, s4, 7
	s_and_b32 s98, s98, 14
	s_bfe_u32 s99, s4, 0x10006
	s_or_b32 s98, s98, s99
	v_sub_u32_e32 v230, s98, v1
	s_lshr_b32 s98, s4, 11
	s_lshl_b32 s98, s98, 11
	s_and_b32 s99, s4, 32
	s_lshl_b32 s99, s99, 4
	s_add_i32 s98, s98, s99
	s_addk_i32 s98, 0x3000
	v_lshl_add_u32 v228, v143, 7, s98
	v_lshl_add_u32 v228, v1, 3, v228
	v_mad_i32_i24 v228, v230, s33, v228
	v_ashrrev_i32_e32 v229, 31, v228
	v_lshl_add_u64 v[232:233], s[68:69], 0, v[228:229]
	v_mul_f32_e32 v158, 0xbfb8aa3b, v158
	v_mul_f32_e32 v156, 0xbfb8aa3b, v156
	v_mul_f32_e32 v152, 0xbfb8aa3b, v152
	v_mul_f32_e32 v150, 0xbfb8aa3b, v150
	v_mul_f32_e32 v148, 0xbfb8aa3b, v148
	v_mul_f32_e32 v146, 0xbfb8aa3b, v146
	v_mul_f32_e32 v144, 0xbfb8aa3b, v144
	v_mul_f32_e32 v142, 0xbfb8aa3b, v142
	v_mad_i64_i32 v[238:239], s[4:5], v154, s33, v[232:233]
	v_pk_mul_f32 v[126:127], v[126:127], v[158:159] op_sel_hi:[1,0]
	v_pk_mul_f32 v[128:129], v[128:129], v[158:159] op_sel_hi:[1,0]
	v_pk_mul_f32 v[122:123], v[122:123], v[158:159] op_sel_hi:[1,0]
	v_pk_mul_f32 v[124:125], v[124:125], v[158:159] op_sel_hi:[1,0]
	v_exp_f32_e32 v126, v126
	v_exp_f32_e32 v127, v127
	v_exp_f32_e32 v128, v128
	v_exp_f32_e32 v129, v129
	v_exp_f32_e32 v122, v122
	v_exp_f32_e32 v123, v123
	v_exp_f32_e32 v124, v124
	v_exp_f32_e32 v125, v125
	v_pk_add_f32 v[126:127], v[126:127], 1.0 op_sel_hi:[1,0]
	v_pk_add_f32 v[128:129], v[128:129], 1.0 op_sel_hi:[1,0]
	v_pk_add_f32 v[122:123], v[122:123], 1.0 op_sel_hi:[1,0]
	v_pk_add_f32 v[124:125], v[124:125], 1.0 op_sel_hi:[1,0]
	v_rcp_f32_e32 v126, v126
	v_rcp_f32_e32 v127, v127
	v_rcp_f32_e32 v128, v128
	v_rcp_f32_e32 v129, v129
	v_rcp_f32_e32 v122, v122
	v_rcp_f32_e32 v123, v123
	v_rcp_f32_e32 v124, v124
	v_rcp_f32_e32 v125, v125
	v_pk_fma_f32 v[126:127], v[126:127], s[8:9], 0.5 op_sel_hi:[1,0,0]
	v_pk_fma_f32 v[128:129], v[128:129], s[8:9], 0.5 op_sel_hi:[1,0,0]
	v_pk_fma_f32 v[122:123], v[122:123], s[8:9], 0.5 op_sel_hi:[1,0,0]
	v_pk_fma_f32 v[124:125], v[124:125], s[8:9], 0.5 op_sel_hi:[1,0,0]
	v_cvt_u32_f32_e32 v234, v126
	v_cvt_u32_f32_e32 v235, v122
	v_cvt_u32_f32_sdwa v234, v127 dst_sel:BYTE_1 dst_unused:UNUSED_PRESERVE src0_sel:DWORD
	v_cvt_u32_f32_sdwa v235, v123 dst_sel:BYTE_1 dst_unused:UNUSED_PRESERVE src0_sel:DWORD
	v_cvt_u32_f32_sdwa v234, v128 dst_sel:BYTE_2 dst_unused:UNUSED_PRESERVE src0_sel:DWORD
	v_cvt_u32_f32_sdwa v235, v124 dst_sel:BYTE_2 dst_unused:UNUSED_PRESERVE src0_sel:DWORD
	v_cvt_u32_f32_sdwa v234, v129 dst_sel:BYTE_3 dst_unused:UNUSED_PRESERVE src0_sel:DWORD
	v_cvt_u32_f32_sdwa v235, v125 dst_sel:BYTE_3 dst_unused:UNUSED_PRESERVE src0_sel:DWORD
	s_nop 1
	global_store_dwordx2 v[238:239], v[234:235], off
	v_pk_mul_f32 v[118:119], v[118:119], v[158:159] op_sel_hi:[1,0]
	v_pk_mul_f32 v[120:121], v[120:121], v[158:159] op_sel_hi:[1,0]
	v_pk_mul_f32 v[110:111], v[110:111], v[158:159] op_sel_hi:[1,0]
	v_pk_mul_f32 v[112:113], v[112:113], v[158:159] op_sel_hi:[1,0]
	v_exp_f32_e32 v118, v118
	v_exp_f32_e32 v119, v119
	v_exp_f32_e32 v120, v120
	v_exp_f32_e32 v121, v121
	v_exp_f32_e32 v110, v110
	v_exp_f32_e32 v111, v111
	v_exp_f32_e32 v112, v112
	v_exp_f32_e32 v113, v113
	v_pk_add_f32 v[118:119], v[118:119], 1.0 op_sel_hi:[1,0]
	v_pk_add_f32 v[120:121], v[120:121], 1.0 op_sel_hi:[1,0]
	v_pk_add_f32 v[110:111], v[110:111], 1.0 op_sel_hi:[1,0]
	v_pk_add_f32 v[112:113], v[112:113], 1.0 op_sel_hi:[1,0]
	v_rcp_f32_e32 v118, v118
	v_rcp_f32_e32 v119, v119
	v_rcp_f32_e32 v120, v120
	v_rcp_f32_e32 v121, v121
	v_rcp_f32_e32 v110, v110
	v_rcp_f32_e32 v111, v111
	v_rcp_f32_e32 v112, v112
	v_rcp_f32_e32 v113, v113
	v_pk_fma_f32 v[118:119], v[118:119], s[8:9], 0.5 op_sel_hi:[1,0,0]
	v_pk_fma_f32 v[120:121], v[120:121], s[8:9], 0.5 op_sel_hi:[1,0,0]
	v_pk_fma_f32 v[110:111], v[110:111], s[8:9], 0.5 op_sel_hi:[1,0,0]
	v_pk_fma_f32 v[112:113], v[112:113], s[8:9], 0.5 op_sel_hi:[1,0,0]
	v_cvt_u32_f32_e32 v236, v118
	v_cvt_u32_f32_e32 v237, v110
	v_cvt_u32_f32_sdwa v236, v119 dst_sel:BYTE_1 dst_unused:UNUSED_PRESERVE src0_sel:DWORD
	v_cvt_u32_f32_sdwa v237, v111 dst_sel:BYTE_1 dst_unused:UNUSED_PRESERVE src0_sel:DWORD
	v_cvt_u32_f32_sdwa v236, v120 dst_sel:BYTE_2 dst_unused:UNUSED_PRESERVE src0_sel:DWORD
	v_cvt_u32_f32_sdwa v237, v112 dst_sel:BYTE_2 dst_unused:UNUSED_PRESERVE src0_sel:DWORD
	v_cvt_u32_f32_sdwa v236, v121 dst_sel:BYTE_3 dst_unused:UNUSED_PRESERVE src0_sel:DWORD
	v_cvt_u32_f32_sdwa v237, v113 dst_sel:BYTE_3 dst_unused:UNUSED_PRESERVE src0_sel:DWORD
; __device__ __forceinline__ unsigned cvt_pk_bf16(float lo, float hi) { const bf16x2_t r = __builtin_convertvector((f32x2){lo, hi}, bf16x2_t); return __builtin_bit_cast(unsigned, r); }
; __device__ __forceinline__ float bf_lo(unsigned u) { return __uint_as_float(u << 16); }
; __device__ __forceinline__ float bf_hi(unsigned u) { return __uint_as_float(u & 0xffff0000u); }
; __device__ __forceinline__ float sigmoid_f(float x) { return __builtin_amdgcn_rcpf(1.0f + __builtin_amdgcn_exp2f(-1.4426950409f * x)); }
; __device__ __forceinline__ float silu_f(float x) { return x * sigmoid_f(x); }
; __device__ __forceinline__ u32x4 pack8(f32x4 a, f32x4 b) { u32x4 w; w.x = cvt_pk_bf16(a[0], a[1]); w.y = cvt_pk_bf16(a[2], a[3]); w.z = cvt_pk_bf16(b[0], b[1]); w.w = cvt_pk_bf16(b[2], b[3]); return w; }
; __device__ __forceinline__ void unpack8(u32x4 g, f32x4& a, f32x4& b) { a = (f32x4){bf_lo(g.x), bf_hi(g.x), bf_lo(g.y), bf_hi(g.y)}; b = (f32x4){bf_lo(g.z), bf_hi(g.z), bf_lo(g.w), bf_hi(g.w)}; }
;     __device__ __forceinline__ void body_gate(f32x4 (&acc)[2][2][4][2], const Unit& u, int wr, int wc, int fr, int fq, int gbase, const float (&rsv)[2][4]) const {
;     ...
;             for (int bj = 0; bj < 2; ++bj) { if (u.half != 0 && bj == 1) continue;
;                 const int gcol = gbase + (bj + (u.half == 2 ? 1 : 0)) * 128 + wc * 32 + 8 * fq;
;                 f32x4 v0 = acc[ai][bj][m][0] * rs, v1 = acc[ai][bj][m][1] * rs;
; #pragma unroll
;                 for (int j = 0; j < 4; ++j) { v0[j] = sigmoid_f(v0[j]); v1[j] = sigmoid_f(v1[j]); }
;                 u32x2 w; w.x = pk_unorm8(v0); w.y = pk_unorm8(v1);
;                 *(u32x2*)((unsigned char*)P + (size_t)row * ROWB + GATE_B0 + gcol) = w;
	s_nop 1
	global_store_dwordx2 v[238:239], v[236:237], off offset:1024
	v_mad_i64_i32 v[240:241], s[4:5], v209, s33, v[232:233]
	v_pk_mul_f32 v[114:115], v[114:115], v[156:157] op_sel_hi:[1,0]
	v_pk_mul_f32 v[116:117], v[116:117], v[156:157] op_sel_hi:[1,0]
	v_pk_mul_f32 v[106:107], v[106:107], v[156:157] op_sel_hi:[1,0]
	v_pk_mul_f32 v[108:109], v[108:109], v[156:157] op_sel_hi:[1,0]
	v_exp_f32_e32 v114, v114
	v_exp_f32_e32 v115, v115
	v_exp_f32_e32 v116, v116
	v_exp_f32_e32 v117, v117
	v_exp_f32_e32 v106, v106
	v_exp_f32_e32 v107, v107
	v_exp_f32_e32 v108, v108
	v_exp_f32_e32 v109, v109
	v_pk_add_f32 v[114:115], v[114:115], 1.0 op_sel_hi:[1,0]
	v_pk_add_f32 v[116:117], v[116:117], 1.0 op_sel_hi:[1,0]
	v_pk_add_f32 v[106:107], v[106:107], 1.0 op_sel_hi:[1,0]
	v_pk_add_f32 v[108:109], v[108:109], 1.0 op_sel_hi:[1,0]
	v_rcp_f32_e32 v114, v114
	v_rcp_f32_e32 v115, v115
	v_rcp_f32_e32 v116, v116
	v_rcp_f32_e32 v117, v117
	v_rcp_f32_e32 v106, v106
	v_rcp_f32_e32 v107, v107
	v_rcp_f32_e32 v108, v108
	v_rcp_f32_e32 v109, v109
	v_pk_fma_f32 v[114:115], v[114:115], s[8:9], 0.5 op_sel_hi:[1,0,0]
	v_pk_fma_f32 v[116:117], v[116:117], s[8:9], 0.5 op_sel_hi:[1,0,0]
	v_pk_fma_f32 v[106:107], v[106:107], s[8:9], 0.5 op_sel_hi:[1,0,0]
	v_pk_fma_f32 v[108:109], v[108:109], s[8:9], 0.5 op_sel_hi:[1,0,0]
	v_cvt_u32_f32_e32 v234, v114
	v_cvt_u32_f32_e32 v235, v106
	v_cvt_u32_f32_sdwa v234, v115 dst_sel:BYTE_1 dst_unused:UNUSED_PRESERVE src0_sel:DWORD
	v_cvt_u32_f32_sdwa v235, v107 dst_sel:BYTE_1 dst_unused:UNUSED_PRESERVE src0_sel:DWORD
	v_cvt_u32_f32_sdwa v234, v116 dst_sel:BYTE_2 dst_unused:UNUSED_PRESERVE src0_sel:DWORD
	v_cvt_u32_f32_sdwa v235, v108 dst_sel:BYTE_2 dst_unused:UNUSED_PRESERVE src0_sel:DWORD
	v_cvt_u32_f32_sdwa v234, v117 dst_sel:BYTE_3 dst_unused:UNUSED_PRESERVE src0_sel:DWORD
	v_cvt_u32_f32_sdwa v235, v109 dst_sel:BYTE_3 dst_unused:UNUSED_PRESERVE src0_sel:DWORD
	s_nop 1
	global_store_dwordx2 v[240:241], v[234:235], off
	v_pk_mul_f32 v[98:99], v[98:99], v[156:157] op_sel_hi:[1,0]
	v_pk_mul_f32 v[100:101], v[100:101], v[156:157] op_sel_hi:[1,0]
	v_pk_mul_f32 v[90:91], v[90:91], v[156:157] op_sel_hi:[1,0]
	v_pk_mul_f32 v[92:93], v[92:93], v[156:157] op_sel_hi:[1,0]
	v_exp_f32_e32 v98, v98
	v_exp_f32_e32 v99, v99
	v_exp_f32_e32 v100, v100
	v_exp_f32_e32 v101, v101
	v_exp_f32_e32 v90, v90
	v_exp_f32_e32 v91, v91
	v_exp_f32_e32 v92, v92
	v_exp_f32_e32 v93, v93
	v_pk_add_f32 v[98:99], v[98:99], 1.0 op_sel_hi:[1,0]
	v_pk_add_f32 v[100:101], v[100:101], 1.0 op_sel_hi:[1,0]
	v_pk_add_f32 v[90:91], v[90:91], 1.0 op_sel_hi:[1,0]
	v_pk_add_f32 v[92:93], v[92:93], 1.0 op_sel_hi:[1,0]
	v_rcp_f32_e32 v98, v98
	v_rcp_f32_e32 v99, v99
	v_rcp_f32_e32 v100, v100
	v_rcp_f32_e32 v101, v101
	v_rcp_f32_e32 v90, v90
	v_rcp_f32_e32 v91, v91
	v_rcp_f32_e32 v92, v92
	v_rcp_f32_e32 v93, v93
	v_pk_fma_f32 v[98:99], v[98:99], s[8:9], 0.5 op_sel_hi:[1,0,0]
	v_pk_fma_f32 v[100:101], v[100:101], s[8:9], 0.5 op_sel_hi:[1,0,0]
	v_pk_fma_f32 v[90:91], v[90:91], s[8:9], 0.5 op_sel_hi:[1,0,0]
	v_pk_fma_f32 v[92:93], v[92:93], s[8:9], 0.5 op_sel_hi:[1,0,0]
	v_cvt_u32_f32_e32 v236, v98
	v_cvt_u32_f32_e32 v237, v90
	v_cvt_u32_f32_sdwa v236, v99 dst_sel:BYTE_1 dst_unused:UNUSED_PRESERVE src0_sel:DWORD
	v_cvt_u32_f32_sdwa v237, v91 dst_sel:BYTE_1 dst_unused:UNUSED_PRESERVE src0_sel:DWORD
	v_cvt_u32_f32_sdwa v236, v100 dst_sel:BYTE_2 dst_unused:UNUSED_PRESERVE src0_sel:DWORD
	v_cvt_u32_f32_sdwa v237, v92 dst_sel:BYTE_2 dst_unused:UNUSED_PRESERVE src0_sel:DWORD
	v_cvt_u32_f32_sdwa v236, v101 dst_sel:BYTE_3 dst_unused:UNUSED_PRESERVE src0_sel:DWORD
	v_cvt_u32_f32_sdwa v237, v93 dst_sel:BYTE_3 dst_unused:UNUSED_PRESERVE src0_sel:DWORD
	s_nop 1
	global_store_dwordx2 v[240:241], v[236:237], off offset:1024
	v_mad_i64_i32 v[238:239], s[4:5], v208, s33, v[232:233]
	v_pk_mul_f32 v[102:103], v[102:103], v[152:153] op_sel_hi:[1,0]
	v_pk_mul_f32 v[104:105], v[104:105], v[152:153] op_sel_hi:[1,0]
	v_pk_mul_f32 v[94:95], v[94:95], v[152:153] op_sel_hi:[1,0]
	v_pk_mul_f32 v[96:97], v[96:97], v[152:153] op_sel_hi:[1,0]
	v_exp_f32_e32 v102, v102
	v_exp_f32_e32 v103, v103
	v_exp_f32_e32 v104, v104
	v_exp_f32_e32 v105, v105
	v_exp_f32_e32 v94, v94
	v_exp_f32_e32 v95, v95
	v_exp_f32_e32 v96, v96
	v_exp_f32_e32 v97, v97
	v_pk_add_f32 v[102:103], v[102:103], 1.0 op_sel_hi:[1,0]
	v_pk_add_f32 v[104:105], v[104:105], 1.0 op_sel_hi:[1,0]
	v_pk_add_f32 v[94:95], v[94:95], 1.0 op_sel_hi:[1,0]
	v_pk_add_f32 v[96:97], v[96:97], 1.0 op_sel_hi:[1,0]
	v_rcp_f32_e32 v102, v102
	v_rcp_f32_e32 v103, v103
	v_rcp_f32_e32 v104, v104
	v_rcp_f32_e32 v105, v105
	v_rcp_f32_e32 v94, v94
	v_rcp_f32_e32 v95, v95
	v_rcp_f32_e32 v96, v96
	v_rcp_f32_e32 v97, v97
	v_pk_fma_f32 v[102:103], v[102:103], s[8:9], 0.5 op_sel_hi:[1,0,0]
	v_pk_fma_f32 v[104:105], v[104:105], s[8:9], 0.5 op_sel_hi:[1,0,0]
	v_pk_fma_f32 v[94:95], v[94:95], s[8:9], 0.5 op_sel_hi:[1,0,0]
	v_pk_fma_f32 v[96:97], v[96:97], s[8:9], 0.5 op_sel_hi:[1,0,0]
	v_cvt_u32_f32_e32 v234, v102
	v_cvt_u32_f32_e32 v235, v94
	v_cvt_u32_f32_sdwa v234, v103 dst_sel:BYTE_1 dst_unused:UNUSED_PRESERVE src0_sel:DWORD
	v_cvt_u32_f32_sdwa v235, v95 dst_sel:BYTE_1 dst_unused:UNUSED_PRESERVE src0_sel:DWORD
	v_cvt_u32_f32_sdwa v234, v104 dst_sel:BYTE_2 dst_unused:UNUSED_PRESERVE src0_sel:DWORD
	v_cvt_u32_f32_sdwa v235, v96 dst_sel:BYTE_2 dst_unused:UNUSED_PRESERVE src0_sel:DWORD
	v_cvt_u32_f32_sdwa v234, v105 dst_sel:BYTE_3 dst_unused:UNUSED_PRESERVE src0_sel:DWORD
	v_cvt_u32_f32_sdwa v235, v97 dst_sel:BYTE_3 dst_unused:UNUSED_PRESERVE src0_sel:DWORD
	s_nop 1
	global_store_dwordx2 v[238:239], v[234:235], off
	v_pk_mul_f32 v[82:83], v[82:83], v[152:153] op_sel_hi:[1,0]
; __device__ __forceinline__ unsigned cvt_pk_bf16(float lo, float hi) { const bf16x2_t r = __builtin_convertvector((f32x2){lo, hi}, bf16x2_t); return __builtin_bit_cast(unsigned, r); }
; __device__ __forceinline__ float bf_lo(unsigned u) { return __uint_as_float(u << 16); }
; __device__ __forceinline__ float bf_hi(unsigned u) { return __uint_as_float(u & 0xffff0000u); }
; __device__ __forceinline__ float sigmoid_f(float x) { return __builtin_amdgcn_rcpf(1.0f + __builtin_amdgcn_exp2f(-1.4426950409f * x)); }
; __device__ __forceinline__ float silu_f(float x) { return x * sigmoid_f(x); }
; __device__ __forceinline__ u32x4 pack8(f32x4 a, f32x4 b) { u32x4 w; w.x = cvt_pk_bf16(a[0], a[1]); w.y = cvt_pk_bf16(a[2], a[3]); w.z = cvt_pk_bf16(b[0], b[1]); w.w = cvt_pk_bf16(b[2], b[3]); return w; }
; __device__ __forceinline__ void unpack8(u32x4 g, f32x4& a, f32x4& b) { a = (f32x4){bf_lo(g.x), bf_hi(g.x), bf_lo(g.y), bf_hi(g.y)}; b = (f32x4){bf_lo(g.z), bf_hi(g.z), bf_lo(g.w), bf_hi(g.w)}; }
;     __device__ __forceinline__ void body_gate(f32x4 (&acc)[2][2][4][2], const Unit& u, int wr, int wc, int fr, int fq, int gbase, const float (&rsv)[2][4]) const {
;     ...
;             for (int bj = 0; bj < 2; ++bj) { if (u.half != 0 && bj == 1) continue;
;                 const int gcol = gbase + (bj + (u.half == 2 ? 1 : 0)) * 128 + wc * 32 + 8 * fq;
;                 f32x4 v0 = acc[ai][bj][m][0] * rs, v1 = acc[ai][bj][m][1] * rs;
; #pragma unroll
;                 for (int j = 0; j < 4; ++j) { v0[j] = sigmoid_f(v0[j]); v1[j] = sigmoid_f(v1[j]); }
;                 u32x2 w; w.x = pk_unorm8(v0); w.y = pk_unorm8(v1);
;                 *(u32x2*)((unsigned char*)P + (size_t)row * ROWB + GATE_B0 + gcol) = w;
	v_pk_mul_f32 v[84:85], v[84:85], v[152:153] op_sel_hi:[1,0]
	v_pk_mul_f32 v[74:75], v[74:75], v[152:153] op_sel_hi:[1,0]
	v_pk_mul_f32 v[76:77], v[76:77], v[152:153] op_sel_hi:[1,0]
	v_exp_f32_e32 v82, v82
	v_exp_f32_e32 v83, v83
	v_exp_f32_e32 v84, v84
	v_exp_f32_e32 v85, v85
	v_exp_f32_e32 v74, v74
	v_exp_f32_e32 v75, v75
	v_exp_f32_e32 v76, v76
	v_exp_f32_e32 v77, v77
	v_pk_add_f32 v[82:83], v[82:83], 1.0 op_sel_hi:[1,0]
	v_pk_add_f32 v[84:85], v[84:85], 1.0 op_sel_hi:[1,0]
	v_pk_add_f32 v[74:75], v[74:75], 1.0 op_sel_hi:[1,0]
	v_pk_add_f32 v[76:77], v[76:77], 1.0 op_sel_hi:[1,0]
	v_rcp_f32_e32 v82, v82
	v_rcp_f32_e32 v83, v83
	v_rcp_f32_e32 v84, v84
	v_rcp_f32_e32 v85, v85
	v_rcp_f32_e32 v74, v74
	v_rcp_f32_e32 v75, v75
	v_rcp_f32_e32 v76, v76
	v_rcp_f32_e32 v77, v77
	v_pk_fma_f32 v[82:83], v[82:83], s[8:9], 0.5 op_sel_hi:[1,0,0]
	v_pk_fma_f32 v[84:85], v[84:85], s[8:9], 0.5 op_sel_hi:[1,0,0]
	v_pk_fma_f32 v[74:75], v[74:75], s[8:9], 0.5 op_sel_hi:[1,0,0]
	v_pk_fma_f32 v[76:77], v[76:77], s[8:9], 0.5 op_sel_hi:[1,0,0]
	v_cvt_u32_f32_e32 v236, v82
	v_cvt_u32_f32_e32 v237, v74
	v_cvt_u32_f32_sdwa v236, v83 dst_sel:BYTE_1 dst_unused:UNUSED_PRESERVE src0_sel:DWORD
	v_cvt_u32_f32_sdwa v237, v75 dst_sel:BYTE_1 dst_unused:UNUSED_PRESERVE src0_sel:DWORD
	v_cvt_u32_f32_sdwa v236, v84 dst_sel:BYTE_2 dst_unused:UNUSED_PRESERVE src0_sel:DWORD
	v_cvt_u32_f32_sdwa v237, v76 dst_sel:BYTE_2 dst_unused:UNUSED_PRESERVE src0_sel:DWORD
	v_cvt_u32_f32_sdwa v236, v85 dst_sel:BYTE_3 dst_unused:UNUSED_PRESERVE src0_sel:DWORD
	v_cvt_u32_f32_sdwa v237, v77 dst_sel:BYTE_3 dst_unused:UNUSED_PRESERVE src0_sel:DWORD
	s_nop 1
	global_store_dwordx2 v[238:239], v[236:237], off offset:1024
	v_mad_i64_i32 v[240:241], s[4:5], v157, s33, v[232:233]
	v_pk_mul_f32 v[86:87], v[86:87], v[150:151] op_sel_hi:[1,0]
	v_pk_mul_f32 v[88:89], v[88:89], v[150:151] op_sel_hi:[1,0]
	v_pk_mul_f32 v[78:79], v[78:79], v[150:151] op_sel_hi:[1,0]
	v_pk_mul_f32 v[80:81], v[80:81], v[150:151] op_sel_hi:[1,0]
	v_exp_f32_e32 v86, v86
	v_exp_f32_e32 v87, v87
	v_exp_f32_e32 v88, v88
	v_exp_f32_e32 v89, v89
	v_exp_f32_e32 v78, v78
	v_exp_f32_e32 v79, v79
	v_exp_f32_e32 v80, v80
	v_exp_f32_e32 v81, v81
	v_pk_add_f32 v[86:87], v[86:87], 1.0 op_sel_hi:[1,0]
	v_pk_add_f32 v[88:89], v[88:89], 1.0 op_sel_hi:[1,0]
	v_pk_add_f32 v[78:79], v[78:79], 1.0 op_sel_hi:[1,0]
	v_pk_add_f32 v[80:81], v[80:81], 1.0 op_sel_hi:[1,0]
	v_rcp_f32_e32 v86, v86
	v_rcp_f32_e32 v87, v87
	v_rcp_f32_e32 v88, v88
	v_rcp_f32_e32 v89, v89
	v_rcp_f32_e32 v78, v78
	v_rcp_f32_e32 v79, v79
	v_rcp_f32_e32 v80, v80
	v_rcp_f32_e32 v81, v81
	v_pk_fma_f32 v[86:87], v[86:87], s[8:9], 0.5 op_sel_hi:[1,0,0]
	v_pk_fma_f32 v[88:89], v[88:89], s[8:9], 0.5 op_sel_hi:[1,0,0]
	v_pk_fma_f32 v[78:79], v[78:79], s[8:9], 0.5 op_sel_hi:[1,0,0]
	v_pk_fma_f32 v[80:81], v[80:81], s[8:9], 0.5 op_sel_hi:[1,0,0]
	v_cvt_u32_f32_e32 v234, v86
	v_cvt_u32_f32_e32 v235, v78
	v_cvt_u32_f32_sdwa v234, v87 dst_sel:BYTE_1 dst_unused:UNUSED_PRESERVE src0_sel:DWORD
	v_cvt_u32_f32_sdwa v235, v79 dst_sel:BYTE_1 dst_unused:UNUSED_PRESERVE src0_sel:DWORD
	v_cvt_u32_f32_sdwa v234, v88 dst_sel:BYTE_2 dst_unused:UNUSED_PRESERVE src0_sel:DWORD
	v_cvt_u32_f32_sdwa v235, v80 dst_sel:BYTE_2 dst_unused:UNUSED_PRESERVE src0_sel:DWORD
	v_cvt_u32_f32_sdwa v234, v89 dst_sel:BYTE_3 dst_unused:UNUSED_PRESERVE src0_sel:DWORD
	v_cvt_u32_f32_sdwa v235, v81 dst_sel:BYTE_3 dst_unused:UNUSED_PRESERVE src0_sel:DWORD
	s_nop 1
	global_store_dwordx2 v[240:241], v[234:235], off
	v_pk_mul_f32 v[70:71], v[70:71], v[150:151] op_sel_hi:[1,0]
	v_pk_mul_f32 v[72:73], v[72:73], v[150:151] op_sel_hi:[1,0]
	v_pk_mul_f32 v[66:67], v[66:67], v[150:151] op_sel_hi:[1,0]
	v_pk_mul_f32 v[68:69], v[68:69], v[150:151] op_sel_hi:[1,0]
	v_exp_f32_e32 v70, v70
	v_exp_f32_e32 v71, v71
	v_exp_f32_e32 v72, v72
	v_exp_f32_e32 v73, v73
	v_exp_f32_e32 v66, v66
	v_exp_f32_e32 v67, v67
	v_exp_f32_e32 v68, v68
	v_exp_f32_e32 v69, v69
	v_pk_add_f32 v[70:71], v[70:71], 1.0 op_sel_hi:[1,0]
	v_pk_add_f32 v[72:73], v[72:73], 1.0 op_sel_hi:[1,0]
	v_pk_add_f32 v[66:67], v[66:67], 1.0 op_sel_hi:[1,0]
	v_pk_add_f32 v[68:69], v[68:69], 1.0 op_sel_hi:[1,0]
	v_rcp_f32_e32 v70, v70
	v_rcp_f32_e32 v71, v71
	v_rcp_f32_e32 v72, v72
	v_rcp_f32_e32 v73, v73
	v_rcp_f32_e32 v66, v66
	v_rcp_f32_e32 v67, v67
	v_rcp_f32_e32 v68, v68
	v_rcp_f32_e32 v69, v69
	v_pk_fma_f32 v[70:71], v[70:71], s[8:9], 0.5 op_sel_hi:[1,0,0]
	v_pk_fma_f32 v[72:73], v[72:73], s[8:9], 0.5 op_sel_hi:[1,0,0]
	v_pk_fma_f32 v[66:67], v[66:67], s[8:9], 0.5 op_sel_hi:[1,0,0]
	v_pk_fma_f32 v[68:69], v[68:69], s[8:9], 0.5 op_sel_hi:[1,0,0]
	v_cvt_u32_f32_e32 v236, v70
	v_cvt_u32_f32_e32 v237, v66
	v_cvt_u32_f32_sdwa v236, v71 dst_sel:BYTE_1 dst_unused:UNUSED_PRESERVE src0_sel:DWORD
	v_cvt_u32_f32_sdwa v237, v67 dst_sel:BYTE_1 dst_unused:UNUSED_PRESERVE src0_sel:DWORD
	v_cvt_u32_f32_sdwa v236, v72 dst_sel:BYTE_2 dst_unused:UNUSED_PRESERVE src0_sel:DWORD
	v_cvt_u32_f32_sdwa v237, v68 dst_sel:BYTE_2 dst_unused:UNUSED_PRESERVE src0_sel:DWORD
	v_cvt_u32_f32_sdwa v236, v73 dst_sel:BYTE_3 dst_unused:UNUSED_PRESERVE src0_sel:DWORD
	v_cvt_u32_f32_sdwa v237, v69 dst_sel:BYTE_3 dst_unused:UNUSED_PRESERVE src0_sel:DWORD
	s_nop 1
	global_store_dwordx2 v[240:241], v[236:237], off offset:1024
	v_mad_i64_i32 v[238:239], s[4:5], v155, s33, v[232:233]
	v_pk_mul_f32 v[62:63], v[62:63], v[148:149] op_sel_hi:[1,0]
	v_pk_mul_f32 v[64:65], v[64:65], v[148:149] op_sel_hi:[1,0]
	v_pk_mul_f32 v[58:59], v[58:59], v[148:149] op_sel_hi:[1,0]
	v_pk_mul_f32 v[60:61], v[60:61], v[148:149] op_sel_hi:[1,0]
	v_exp_f32_e32 v62, v62
	v_exp_f32_e32 v63, v63
	v_exp_f32_e32 v64, v64
	v_exp_f32_e32 v65, v65
; __device__ __forceinline__ unsigned cvt_pk_bf16(float lo, float hi) { const bf16x2_t r = __builtin_convertvector((f32x2){lo, hi}, bf16x2_t); return __builtin_bit_cast(unsigned, r); }
; __device__ __forceinline__ float bf_lo(unsigned u) { return __uint_as_float(u << 16); }
; __device__ __forceinline__ float bf_hi(unsigned u) { return __uint_as_float(u & 0xffff0000u); }
; __device__ __forceinline__ float sigmoid_f(float x) { return __builtin_amdgcn_rcpf(1.0f + __builtin_amdgcn_exp2f(-1.4426950409f * x)); }
; __device__ __forceinline__ float silu_f(float x) { return x * sigmoid_f(x); }
; __device__ __forceinline__ u32x4 pack8(f32x4 a, f32x4 b) { u32x4 w; w.x = cvt_pk_bf16(a[0], a[1]); w.y = cvt_pk_bf16(a[2], a[3]); w.z = cvt_pk_bf16(b[0], b[1]); w.w = cvt_pk_bf16(b[2], b[3]); return w; }
; __device__ __forceinline__ void unpack8(u32x4 g, f32x4& a, f32x4& b) { a = (f32x4){bf_lo(g.x), bf_hi(g.x), bf_lo(g.y), bf_hi(g.y)}; b = (f32x4){bf_lo(g.z), bf_hi(g.z), bf_lo(g.w), bf_hi(g.w)}; }
;     __device__ __forceinline__ void body_gate(f32x4 (&acc)[2][2][4][2], const Unit& u, int wr, int wc, int fr, int fq, int gbase, const float (&rsv)[2][4]) const {
;     ...
;             for (int bj = 0; bj < 2; ++bj) { if (u.half != 0 && bj == 1) continue;
;                 const int gcol = gbase + (bj + (u.half == 2 ? 1 : 0)) * 128 + wc * 32 + 8 * fq;
;                 f32x4 v0 = acc[ai][bj][m][0] * rs, v1 = acc[ai][bj][m][1] * rs;
; #pragma unroll
;                 for (int j = 0; j < 4; ++j) { v0[j] = sigmoid_f(v0[j]); v1[j] = sigmoid_f(v1[j]); }
;                 u32x2 w; w.x = pk_unorm8(v0); w.y = pk_unorm8(v1);
;                 *(u32x2*)((unsigned char*)P + (size_t)row * ROWB + GATE_B0 + gcol) = w;
	v_exp_f32_e32 v58, v58
	v_exp_f32_e32 v59, v59
	v_exp_f32_e32 v60, v60
	v_exp_f32_e32 v61, v61
	v_pk_add_f32 v[62:63], v[62:63], 1.0 op_sel_hi:[1,0]
	v_pk_add_f32 v[64:65], v[64:65], 1.0 op_sel_hi:[1,0]
	v_pk_add_f32 v[58:59], v[58:59], 1.0 op_sel_hi:[1,0]
	v_pk_add_f32 v[60:61], v[60:61], 1.0 op_sel_hi:[1,0]
	v_rcp_f32_e32 v62, v62
	v_rcp_f32_e32 v63, v63
	v_rcp_f32_e32 v64, v64
	v_rcp_f32_e32 v65, v65
	v_rcp_f32_e32 v58, v58
	v_rcp_f32_e32 v59, v59
	v_rcp_f32_e32 v60, v60
	v_rcp_f32_e32 v61, v61
	v_pk_fma_f32 v[62:63], v[62:63], s[8:9], 0.5 op_sel_hi:[1,0,0]
	v_pk_fma_f32 v[64:65], v[64:65], s[8:9], 0.5 op_sel_hi:[1,0,0]
	v_pk_fma_f32 v[58:59], v[58:59], s[8:9], 0.5 op_sel_hi:[1,0,0]
	v_pk_fma_f32 v[60:61], v[60:61], s[8:9], 0.5 op_sel_hi:[1,0,0]
	v_cvt_u32_f32_e32 v234, v62
	v_cvt_u32_f32_e32 v235, v58
	v_cvt_u32_f32_sdwa v234, v63 dst_sel:BYTE_1 dst_unused:UNUSED_PRESERVE src0_sel:DWORD
	v_cvt_u32_f32_sdwa v235, v59 dst_sel:BYTE_1 dst_unused:UNUSED_PRESERVE src0_sel:DWORD
	v_cvt_u32_f32_sdwa v234, v64 dst_sel:BYTE_2 dst_unused:UNUSED_PRESERVE src0_sel:DWORD
	v_cvt_u32_f32_sdwa v235, v60 dst_sel:BYTE_2 dst_unused:UNUSED_PRESERVE src0_sel:DWORD
	v_cvt_u32_f32_sdwa v234, v65 dst_sel:BYTE_3 dst_unused:UNUSED_PRESERVE src0_sel:DWORD
	v_cvt_u32_f32_sdwa v235, v61 dst_sel:BYTE_3 dst_unused:UNUSED_PRESERVE src0_sel:DWORD
	s_nop 1
	global_store_dwordx2 v[238:239], v[234:235], off
	v_pk_mul_f32 v[50:51], v[50:51], v[148:149] op_sel_hi:[1,0]
	v_pk_mul_f32 v[52:53], v[52:53], v[148:149] op_sel_hi:[1,0]
	v_pk_mul_f32 v[42:43], v[42:43], v[148:149] op_sel_hi:[1,0]
	v_pk_mul_f32 v[44:45], v[44:45], v[148:149] op_sel_hi:[1,0]
	v_exp_f32_e32 v50, v50
	v_exp_f32_e32 v51, v51
	v_exp_f32_e32 v52, v52
	v_exp_f32_e32 v53, v53
	v_exp_f32_e32 v42, v42
	v_exp_f32_e32 v43, v43
	v_exp_f32_e32 v44, v44
	v_exp_f32_e32 v45, v45
	v_pk_add_f32 v[50:51], v[50:51], 1.0 op_sel_hi:[1,0]
	v_pk_add_f32 v[52:53], v[52:53], 1.0 op_sel_hi:[1,0]
	v_pk_add_f32 v[42:43], v[42:43], 1.0 op_sel_hi:[1,0]
	v_pk_add_f32 v[44:45], v[44:45], 1.0 op_sel_hi:[1,0]
	v_rcp_f32_e32 v50, v50
	v_rcp_f32_e32 v51, v51
	v_rcp_f32_e32 v52, v52
	v_rcp_f32_e32 v53, v53
	v_rcp_f32_e32 v42, v42
	v_rcp_f32_e32 v43, v43
	v_rcp_f32_e32 v44, v44
	v_rcp_f32_e32 v45, v45
	v_pk_fma_f32 v[50:51], v[50:51], s[8:9], 0.5 op_sel_hi:[1,0,0]
	v_pk_fma_f32 v[52:53], v[52:53], s[8:9], 0.5 op_sel_hi:[1,0,0]
	v_pk_fma_f32 v[42:43], v[42:43], s[8:9], 0.5 op_sel_hi:[1,0,0]
	v_pk_fma_f32 v[44:45], v[44:45], s[8:9], 0.5 op_sel_hi:[1,0,0]
	v_cvt_u32_f32_e32 v236, v50
	v_cvt_u32_f32_e32 v237, v42
	v_cvt_u32_f32_sdwa v236, v51 dst_sel:BYTE_1 dst_unused:UNUSED_PRESERVE src0_sel:DWORD
	v_cvt_u32_f32_sdwa v237, v43 dst_sel:BYTE_1 dst_unused:UNUSED_PRESERVE src0_sel:DWORD
	v_cvt_u32_f32_sdwa v236, v52 dst_sel:BYTE_2 dst_unused:UNUSED_PRESERVE src0_sel:DWORD
	v_cvt_u32_f32_sdwa v237, v44 dst_sel:BYTE_2 dst_unused:UNUSED_PRESERVE src0_sel:DWORD
	v_cvt_u32_f32_sdwa v236, v53 dst_sel:BYTE_3 dst_unused:UNUSED_PRESERVE src0_sel:DWORD
	v_cvt_u32_f32_sdwa v237, v45 dst_sel:BYTE_3 dst_unused:UNUSED_PRESERVE src0_sel:DWORD
	s_nop 1
	global_store_dwordx2 v[238:239], v[236:237], off offset:1024
	v_mad_i64_i32 v[240:241], s[4:5], v153, s33, v[232:233]
	v_pk_mul_f32 v[54:55], v[54:55], v[146:147] op_sel_hi:[1,0]
	v_pk_mul_f32 v[56:57], v[56:57], v[146:147] op_sel_hi:[1,0]
	v_pk_mul_f32 v[46:47], v[46:47], v[146:147] op_sel_hi:[1,0]
	v_pk_mul_f32 v[48:49], v[48:49], v[146:147] op_sel_hi:[1,0]
	v_exp_f32_e32 v54, v54
	v_exp_f32_e32 v55, v55
	v_exp_f32_e32 v56, v56
	v_exp_f32_e32 v57, v57
	v_exp_f32_e32 v46, v46
	v_exp_f32_e32 v47, v47
	v_exp_f32_e32 v48, v48
	v_exp_f32_e32 v49, v49
	v_pk_add_f32 v[54:55], v[54:55], 1.0 op_sel_hi:[1,0]
	v_pk_add_f32 v[56:57], v[56:57], 1.0 op_sel_hi:[1,0]
	v_pk_add_f32 v[46:47], v[46:47], 1.0 op_sel_hi:[1,0]
	v_pk_add_f32 v[48:49], v[48:49], 1.0 op_sel_hi:[1,0]
	v_rcp_f32_e32 v54, v54
	v_rcp_f32_e32 v55, v55
	v_rcp_f32_e32 v56, v56
	v_rcp_f32_e32 v57, v57
	v_rcp_f32_e32 v46, v46
	v_rcp_f32_e32 v47, v47
	v_rcp_f32_e32 v48, v48
	v_rcp_f32_e32 v49, v49
	v_pk_fma_f32 v[54:55], v[54:55], s[8:9], 0.5 op_sel_hi:[1,0,0]
	v_pk_fma_f32 v[56:57], v[56:57], s[8:9], 0.5 op_sel_hi:[1,0,0]
	v_pk_fma_f32 v[46:47], v[46:47], s[8:9], 0.5 op_sel_hi:[1,0,0]
	v_pk_fma_f32 v[48:49], v[48:49], s[8:9], 0.5 op_sel_hi:[1,0,0]
	v_cvt_u32_f32_e32 v234, v54
	v_cvt_u32_f32_e32 v235, v46
	v_cvt_u32_f32_sdwa v234, v55 dst_sel:BYTE_1 dst_unused:UNUSED_PRESERVE src0_sel:DWORD
	v_cvt_u32_f32_sdwa v235, v47 dst_sel:BYTE_1 dst_unused:UNUSED_PRESERVE src0_sel:DWORD
	v_cvt_u32_f32_sdwa v234, v56 dst_sel:BYTE_2 dst_unused:UNUSED_PRESERVE src0_sel:DWORD
	v_cvt_u32_f32_sdwa v235, v48 dst_sel:BYTE_2 dst_unused:UNUSED_PRESERVE src0_sel:DWORD
	v_cvt_u32_f32_sdwa v234, v57 dst_sel:BYTE_3 dst_unused:UNUSED_PRESERVE src0_sel:DWORD
	v_cvt_u32_f32_sdwa v235, v49 dst_sel:BYTE_3 dst_unused:UNUSED_PRESERVE src0_sel:DWORD
	s_nop 1
	global_store_dwordx2 v[240:241], v[234:235], off
	v_pk_mul_f32 v[34:35], v[34:35], v[146:147] op_sel_hi:[1,0]
	v_pk_mul_f32 v[36:37], v[36:37], v[146:147] op_sel_hi:[1,0]
	v_pk_mul_f32 v[26:27], v[26:27], v[146:147] op_sel_hi:[1,0]
	v_pk_mul_f32 v[28:29], v[28:29], v[146:147] op_sel_hi:[1,0]
	v_exp_f32_e32 v34, v34
	v_exp_f32_e32 v35, v35
	v_exp_f32_e32 v36, v36
	v_exp_f32_e32 v37, v37
	v_exp_f32_e32 v26, v26
	v_exp_f32_e32 v27, v27
	v_exp_f32_e32 v28, v28
	v_exp_f32_e32 v29, v29
	v_pk_add_f32 v[34:35], v[34:35], 1.0 op_sel_hi:[1,0]
	v_pk_add_f32 v[36:37], v[36:37], 1.0 op_sel_hi:[1,0]
	v_pk_add_f32 v[26:27], v[26:27], 1.0 op_sel_hi:[1,0]
	v_pk_add_f32 v[28:29], v[28:29], 1.0 op_sel_hi:[1,0]
	v_rcp_f32_e32 v34, v34
	v_rcp_f32_e32 v35, v35
; __device__ __forceinline__ unsigned cvt_pk_bf16(float lo, float hi) { const bf16x2_t r = __builtin_convertvector((f32x2){lo, hi}, bf16x2_t); return __builtin_bit_cast(unsigned, r); }
; __device__ __forceinline__ float bf_lo(unsigned u) { return __uint_as_float(u << 16); }
; __device__ __forceinline__ float bf_hi(unsigned u) { return __uint_as_float(u & 0xffff0000u); }
; __device__ __forceinline__ float sigmoid_f(float x) { return __builtin_amdgcn_rcpf(1.0f + __builtin_amdgcn_exp2f(-1.4426950409f * x)); }
; __device__ __forceinline__ float silu_f(float x) { return x * sigmoid_f(x); }
; __device__ __forceinline__ u32x4 pack8(f32x4 a, f32x4 b) { u32x4 w; w.x = cvt_pk_bf16(a[0], a[1]); w.y = cvt_pk_bf16(a[2], a[3]); w.z = cvt_pk_bf16(b[0], b[1]); w.w = cvt_pk_bf16(b[2], b[3]); return w; }
; __device__ __forceinline__ void unpack8(u32x4 g, f32x4& a, f32x4& b) { a = (f32x4){bf_lo(g.x), bf_hi(g.x), bf_lo(g.y), bf_hi(g.y)}; b = (f32x4){bf_lo(g.z), bf_hi(g.z), bf_lo(g.w), bf_hi(g.w)}; }
;     __device__ __forceinline__ void body_gate(f32x4 (&acc)[2][2][4][2], const Unit& u, int wr, int wc, int fr, int fq, int gbase, const float (&rsv)[2][4]) const {
;     ...
;             for (int bj = 0; bj < 2; ++bj) { if (u.half != 0 && bj == 1) continue;
;                 const int gcol = gbase + (bj + (u.half == 2 ? 1 : 0)) * 128 + wc * 32 + 8 * fq;
;                 f32x4 v0 = acc[ai][bj][m][0] * rs, v1 = acc[ai][bj][m][1] * rs;
; #pragma unroll
;                 for (int j = 0; j < 4; ++j) { v0[j] = sigmoid_f(v0[j]); v1[j] = sigmoid_f(v1[j]); }
;                 u32x2 w; w.x = pk_unorm8(v0); w.y = pk_unorm8(v1);
;                 *(u32x2*)((unsigned char*)P + (size_t)row * ROWB + GATE_B0 + gcol) = w;
	v_rcp_f32_e32 v36, v36
	v_rcp_f32_e32 v37, v37
	v_rcp_f32_e32 v26, v26
	v_rcp_f32_e32 v27, v27
	v_rcp_f32_e32 v28, v28
	v_rcp_f32_e32 v29, v29
	v_pk_fma_f32 v[34:35], v[34:35], s[8:9], 0.5 op_sel_hi:[1,0,0]
	v_pk_fma_f32 v[36:37], v[36:37], s[8:9], 0.5 op_sel_hi:[1,0,0]
	v_pk_fma_f32 v[26:27], v[26:27], s[8:9], 0.5 op_sel_hi:[1,0,0]
	v_pk_fma_f32 v[28:29], v[28:29], s[8:9], 0.5 op_sel_hi:[1,0,0]
	v_cvt_u32_f32_e32 v236, v34
	v_cvt_u32_f32_e32 v237, v26
	v_cvt_u32_f32_sdwa v236, v35 dst_sel:BYTE_1 dst_unused:UNUSED_PRESERVE src0_sel:DWORD
	v_cvt_u32_f32_sdwa v237, v27 dst_sel:BYTE_1 dst_unused:UNUSED_PRESERVE src0_sel:DWORD
	v_cvt_u32_f32_sdwa v236, v36 dst_sel:BYTE_2 dst_unused:UNUSED_PRESERVE src0_sel:DWORD
	v_cvt_u32_f32_sdwa v237, v28 dst_sel:BYTE_2 dst_unused:UNUSED_PRESERVE src0_sel:DWORD
	v_cvt_u32_f32_sdwa v236, v37 dst_sel:BYTE_3 dst_unused:UNUSED_PRESERVE src0_sel:DWORD
	v_cvt_u32_f32_sdwa v237, v29 dst_sel:BYTE_3 dst_unused:UNUSED_PRESERVE src0_sel:DWORD
	s_nop 1
	global_store_dwordx2 v[240:241], v[236:237], off offset:1024
	v_mad_i64_i32 v[238:239], s[4:5], v151, s33, v[232:233]
	v_pk_mul_f32 v[38:39], v[38:39], v[144:145] op_sel_hi:[1,0]
	v_pk_mul_f32 v[40:41], v[40:41], v[144:145] op_sel_hi:[1,0]
	v_pk_mul_f32 v[30:31], v[30:31], v[144:145] op_sel_hi:[1,0]
	v_pk_mul_f32 v[32:33], v[32:33], v[144:145] op_sel_hi:[1,0]
	v_exp_f32_e32 v38, v38
	v_exp_f32_e32 v39, v39
	v_exp_f32_e32 v40, v40
	v_exp_f32_e32 v41, v41
	v_exp_f32_e32 v30, v30
	v_exp_f32_e32 v31, v31
	v_exp_f32_e32 v32, v32
	v_exp_f32_e32 v33, v33
	v_pk_add_f32 v[38:39], v[38:39], 1.0 op_sel_hi:[1,0]
	v_pk_add_f32 v[40:41], v[40:41], 1.0 op_sel_hi:[1,0]
	v_pk_add_f32 v[30:31], v[30:31], 1.0 op_sel_hi:[1,0]
	v_pk_add_f32 v[32:33], v[32:33], 1.0 op_sel_hi:[1,0]
	v_rcp_f32_e32 v38, v38
	v_rcp_f32_e32 v39, v39
	v_rcp_f32_e32 v40, v40
	v_rcp_f32_e32 v41, v41
	v_rcp_f32_e32 v30, v30
	v_rcp_f32_e32 v31, v31
	v_rcp_f32_e32 v32, v32
	v_rcp_f32_e32 v33, v33
	v_pk_fma_f32 v[38:39], v[38:39], s[8:9], 0.5 op_sel_hi:[1,0,0]
	v_pk_fma_f32 v[40:41], v[40:41], s[8:9], 0.5 op_sel_hi:[1,0,0]
	v_pk_fma_f32 v[30:31], v[30:31], s[8:9], 0.5 op_sel_hi:[1,0,0]
	v_pk_fma_f32 v[32:33], v[32:33], s[8:9], 0.5 op_sel_hi:[1,0,0]
	v_cvt_u32_f32_e32 v234, v38
	v_cvt_u32_f32_e32 v235, v30
	v_cvt_u32_f32_sdwa v234, v39 dst_sel:BYTE_1 dst_unused:UNUSED_PRESERVE src0_sel:DWORD
	v_cvt_u32_f32_sdwa v235, v31 dst_sel:BYTE_1 dst_unused:UNUSED_PRESERVE src0_sel:DWORD
	v_cvt_u32_f32_sdwa v234, v40 dst_sel:BYTE_2 dst_unused:UNUSED_PRESERVE src0_sel:DWORD
	v_cvt_u32_f32_sdwa v235, v32 dst_sel:BYTE_2 dst_unused:UNUSED_PRESERVE src0_sel:DWORD
	v_cvt_u32_f32_sdwa v234, v41 dst_sel:BYTE_3 dst_unused:UNUSED_PRESERVE src0_sel:DWORD
	v_cvt_u32_f32_sdwa v235, v33 dst_sel:BYTE_3 dst_unused:UNUSED_PRESERVE src0_sel:DWORD
	s_nop 1
	global_store_dwordx2 v[238:239], v[234:235], off
	v_pk_mul_f32 v[18:19], v[18:19], v[144:145] op_sel_hi:[1,0]
	v_pk_mul_f32 v[20:21], v[20:21], v[144:145] op_sel_hi:[1,0]
	v_pk_mul_f32 v[10:11], v[10:11], v[144:145] op_sel_hi:[1,0]
	v_pk_mul_f32 v[12:13], v[12:13], v[144:145] op_sel_hi:[1,0]
	v_exp_f32_e32 v18, v18
	v_exp_f32_e32 v19, v19
	v_exp_f32_e32 v20, v20
	v_exp_f32_e32 v21, v21
	v_exp_f32_e32 v10, v10
	v_exp_f32_e32 v11, v11
	v_exp_f32_e32 v12, v12
	v_exp_f32_e32 v13, v13
	v_pk_add_f32 v[18:19], v[18:19], 1.0 op_sel_hi:[1,0]
	v_pk_add_f32 v[20:21], v[20:21], 1.0 op_sel_hi:[1,0]
	v_pk_add_f32 v[10:11], v[10:11], 1.0 op_sel_hi:[1,0]
	v_pk_add_f32 v[12:13], v[12:13], 1.0 op_sel_hi:[1,0]
	v_rcp_f32_e32 v18, v18
	v_rcp_f32_e32 v19, v19
	v_rcp_f32_e32 v20, v20
	v_rcp_f32_e32 v21, v21
	v_rcp_f32_e32 v10, v10
	v_rcp_f32_e32 v11, v11
	v_rcp_f32_e32 v12, v12
	v_rcp_f32_e32 v13, v13
	v_pk_fma_f32 v[18:19], v[18:19], s[8:9], 0.5 op_sel_hi:[1,0,0]
	v_pk_fma_f32 v[20:21], v[20:21], s[8:9], 0.5 op_sel_hi:[1,0,0]
	v_pk_fma_f32 v[10:11], v[10:11], s[8:9], 0.5 op_sel_hi:[1,0,0]
	v_pk_fma_f32 v[12:13], v[12:13], s[8:9], 0.5 op_sel_hi:[1,0,0]
	v_cvt_u32_f32_e32 v236, v18
	v_cvt_u32_f32_e32 v237, v10
; __device__ __forceinline__ unsigned cvt_pk_bf16(float lo, float hi) { const bf16x2_t r = __builtin_convertvector((f32x2){lo, hi}, bf16x2_t); return __builtin_bit_cast(unsigned, r); }
; __device__ __forceinline__ float bf_lo(unsigned u) { return __uint_as_float(u << 16); }
; __device__ __forceinline__ float bf_hi(unsigned u) { return __uint_as_float(u & 0xffff0000u); }
; __device__ __forceinline__ float sigmoid_f(float x) { return __builtin_amdgcn_rcpf(1.0f + __builtin_amdgcn_exp2f(-1.4426950409f * x)); }
; __device__ __forceinline__ float silu_f(float x) { return x * sigmoid_f(x); }
; __device__ __forceinline__ u32x4 pack8(f32x4 a, f32x4 b) { u32x4 w; w.x = cvt_pk_bf16(a[0], a[1]); w.y = cvt_pk_bf16(a[2], a[3]); w.z = cvt_pk_bf16(b[0], b[1]); w.w = cvt_pk_bf16(b[2], b[3]); return w; }
; __device__ __forceinline__ void unpack8(u32x4 g, f32x4& a, f32x4& b) { a = (f32x4){bf_lo(g.x), bf_hi(g.x), bf_lo(g.y), bf_hi(g.y)}; b = (f32x4){bf_lo(g.z), bf_hi(g.z), bf_lo(g.w), bf_hi(g.w)}; }
;     __device__ __forceinline__ void body_gate(f32x4 (&acc)[2][2][4][2], const Unit& u, int wr, int wc, int fr, int fq, int gbase, const float (&rsv)[2][4]) const {
;         EPI_ROWS_BEGIN
;             const float rs = rsv[ai][m];
; #pragma unroll
;             for (int bj = 0; bj < 2; ++bj) { if (u.half != 0 && bj == 1) continue;
;                 const int gcol = gbase + (bj + (u.half == 2 ? 1 : 0)) * 128 + wc * 32 + 8 * fq;
;                 f32x4 v0 = acc[ai][bj][m][0] * rs, v1 = acc[ai][bj][m][1] * rs;
; #pragma unroll
;                 for (int j = 0; j < 4; ++j) { v0[j] = sigmoid_f(v0[j]); v1[j] = sigmoid_f(v1[j]); }
;                 u32x2 w; w.x = pk_unorm8(v0); w.y = pk_unorm8(v1);
;                 *(u32x2*)((unsigned char*)P + (size_t)row * ROWB + GATE_B0 + gcol) = w;
;             }
;         EPI_END
;     }
	v_cvt_u32_f32_sdwa v236, v19 dst_sel:BYTE_1 dst_unused:UNUSED_PRESERVE src0_sel:DWORD
	v_cvt_u32_f32_sdwa v237, v11 dst_sel:BYTE_1 dst_unused:UNUSED_PRESERVE src0_sel:DWORD
	v_cvt_u32_f32_sdwa v236, v20 dst_sel:BYTE_2 dst_unused:UNUSED_PRESERVE src0_sel:DWORD
	v_cvt_u32_f32_sdwa v237, v12 dst_sel:BYTE_2 dst_unused:UNUSED_PRESERVE src0_sel:DWORD
	v_cvt_u32_f32_sdwa v236, v21 dst_sel:BYTE_3 dst_unused:UNUSED_PRESERVE src0_sel:DWORD
	v_cvt_u32_f32_sdwa v237, v13 dst_sel:BYTE_3 dst_unused:UNUSED_PRESERVE src0_sel:DWORD
	s_nop 1
	global_store_dwordx2 v[238:239], v[236:237], off offset:1024
	v_mad_i64_i32 v[240:241], s[4:5], v149, s33, v[232:233]
	v_pk_mul_f32 v[22:23], v[22:23], v[142:143] op_sel_hi:[1,0]
	v_pk_mul_f32 v[24:25], v[24:25], v[142:143] op_sel_hi:[1,0]
	v_pk_mul_f32 v[14:15], v[14:15], v[142:143] op_sel_hi:[1,0]
	v_pk_mul_f32 v[16:17], v[16:17], v[142:143] op_sel_hi:[1,0]
	v_exp_f32_e32 v22, v22
	v_exp_f32_e32 v23, v23
	v_exp_f32_e32 v24, v24
	v_exp_f32_e32 v25, v25
	v_exp_f32_e32 v14, v14
	v_exp_f32_e32 v15, v15
	v_exp_f32_e32 v16, v16
	v_exp_f32_e32 v17, v17
	v_pk_add_f32 v[22:23], v[22:23], 1.0 op_sel_hi:[1,0]
	v_pk_add_f32 v[24:25], v[24:25], 1.0 op_sel_hi:[1,0]
	v_pk_add_f32 v[14:15], v[14:15], 1.0 op_sel_hi:[1,0]
	v_pk_add_f32 v[16:17], v[16:17], 1.0 op_sel_hi:[1,0]
	v_rcp_f32_e32 v22, v22
	v_rcp_f32_e32 v23, v23
	v_rcp_f32_e32 v24, v24
	v_rcp_f32_e32 v25, v25
	v_rcp_f32_e32 v14, v14
	v_rcp_f32_e32 v15, v15
	v_rcp_f32_e32 v16, v16
	v_rcp_f32_e32 v17, v17
	v_pk_fma_f32 v[22:23], v[22:23], s[8:9], 0.5 op_sel_hi:[1,0,0]
	v_pk_fma_f32 v[24:25], v[24:25], s[8:9], 0.5 op_sel_hi:[1,0,0]
	v_pk_fma_f32 v[14:15], v[14:15], s[8:9], 0.5 op_sel_hi:[1,0,0]
	v_pk_fma_f32 v[16:17], v[16:17], s[8:9], 0.5 op_sel_hi:[1,0,0]
	v_cvt_u32_f32_e32 v234, v22
	v_cvt_u32_f32_e32 v235, v14
	v_cvt_u32_f32_sdwa v234, v23 dst_sel:BYTE_1 dst_unused:UNUSED_PRESERVE src0_sel:DWORD
	v_cvt_u32_f32_sdwa v235, v15 dst_sel:BYTE_1 dst_unused:UNUSED_PRESERVE src0_sel:DWORD
	v_cvt_u32_f32_sdwa v234, v24 dst_sel:BYTE_2 dst_unused:UNUSED_PRESERVE src0_sel:DWORD
	v_cvt_u32_f32_sdwa v235, v16 dst_sel:BYTE_2 dst_unused:UNUSED_PRESERVE src0_sel:DWORD
	v_cvt_u32_f32_sdwa v234, v25 dst_sel:BYTE_3 dst_unused:UNUSED_PRESERVE src0_sel:DWORD
	v_cvt_u32_f32_sdwa v235, v17 dst_sel:BYTE_3 dst_unused:UNUSED_PRESERVE src0_sel:DWORD
	s_nop 1
	global_store_dwordx2 v[240:241], v[234:235], off
	v_pk_mul_f32 v[6:7], v[6:7], v[142:143] op_sel_hi:[1,0]
	v_pk_mul_f32 v[8:9], v[8:9], v[142:143] op_sel_hi:[1,0]
	v_pk_mul_f32 v[2:3], v[2:3], v[142:143] op_sel_hi:[1,0]
	v_pk_mul_f32 v[4:5], v[4:5], v[142:143] op_sel_hi:[1,0]
	v_exp_f32_e32 v6, v6
	v_exp_f32_e32 v7, v7
	v_exp_f32_e32 v8, v8
	v_exp_f32_e32 v9, v9
	v_exp_f32_e32 v2, v2
	v_exp_f32_e32 v3, v3
	v_exp_f32_e32 v4, v4
	v_exp_f32_e32 v5, v5
	v_pk_add_f32 v[6:7], v[6:7], 1.0 op_sel_hi:[1,0]
	v_pk_add_f32 v[8:9], v[8:9], 1.0 op_sel_hi:[1,0]
	v_pk_add_f32 v[2:3], v[2:3], 1.0 op_sel_hi:[1,0]
	v_pk_add_f32 v[4:5], v[4:5], 1.0 op_sel_hi:[1,0]
	v_rcp_f32_e32 v6, v6
	v_rcp_f32_e32 v7, v7
	v_rcp_f32_e32 v8, v8
	v_rcp_f32_e32 v9, v9
	v_rcp_f32_e32 v2, v2
	v_rcp_f32_e32 v3, v3
	v_rcp_f32_e32 v4, v4
	v_rcp_f32_e32 v5, v5
	v_pk_fma_f32 v[6:7], v[6:7], s[8:9], 0.5 op_sel_hi:[1,0,0]
	v_pk_fma_f32 v[8:9], v[8:9], s[8:9], 0.5 op_sel_hi:[1,0,0]
	v_pk_fma_f32 v[2:3], v[2:3], s[8:9], 0.5 op_sel_hi:[1,0,0]
	v_pk_fma_f32 v[4:5], v[4:5], s[8:9], 0.5 op_sel_hi:[1,0,0]
	v_cvt_u32_f32_e32 v236, v6
	v_cvt_u32_f32_e32 v237, v2
	v_cvt_u32_f32_sdwa v236, v7 dst_sel:BYTE_1 dst_unused:UNUSED_PRESERVE src0_sel:DWORD
	v_cvt_u32_f32_sdwa v237, v3 dst_sel:BYTE_1 dst_unused:UNUSED_PRESERVE src0_sel:DWORD
	v_cvt_u32_f32_sdwa v236, v8 dst_sel:BYTE_2 dst_unused:UNUSED_PRESERVE src0_sel:DWORD
	v_cvt_u32_f32_sdwa v237, v4 dst_sel:BYTE_2 dst_unused:UNUSED_PRESERVE src0_sel:DWORD
	v_cvt_u32_f32_sdwa v236, v9 dst_sel:BYTE_3 dst_unused:UNUSED_PRESERVE src0_sel:DWORD
	v_cvt_u32_f32_sdwa v237, v5 dst_sel:BYTE_3 dst_unused:UNUSED_PRESERVE src0_sel:DWORD
	s_nop 1
	global_store_dwordx2 v[240:241], v[236:237], off offset:1024
	s_mov_b64 s[4:5], 0
